# grid barrier: every waiting workgroup polls the TOP arrival counter directly (no XGEN hop through the XCD leader)
# speedup vs baseline: 1.0057x; 1.0024x over previous
.LBB0_181:
	s_lshl_b32 s24, s38, 6
	s_add_i32 s6, s24, 0x500
	s_mov_b32 s7, 0
	s_lshl_b64 s[4:5], s[6:7], 2
	s_add_u32 s4, s36, s4
	s_addc_u32 s5, s37, s5
	v_mov_b32_e32 v1, 1
	v_mov_b64_e32 v[4:5], s[4:5]
	flat_atomic_add v1, v[4:5], v1 sc0
	v_cvt_f32_u32_e32 v3, v2
	v_sub_u32_e32 v4, 0, v2
	v_rcp_iflag_f32_e32 v3, v3
	s_nop 0
	v_mul_f32_e32 v3, 0x4f7ffffe, v3
	v_cvt_u32_f32_e32 v3, v3
	v_mul_lo_u32 v4, v4, v3
	v_mul_hi_u32 v4, v3, v4
	v_add_u32_e32 v3, v3, v4
	s_waitcnt vmcnt(0) lgkmcnt(0)
	v_mul_hi_u32 v3, v1, v3
	v_mul_lo_u32 v5, v3, v2
	v_add_u32_e32 v4, 1, v1
	v_sub_u32_e32 v1, v1, v5
	v_add_u32_e32 v6, 1, v3
	v_cmp_ge_u32_e32 vcc, v1, v2
	v_sub_u32_e32 v5, v1, v2
	s_nop 0
	v_cndmask_b32_e32 v3, v3, v6, vcc
	v_cndmask_b32_e32 v1, v1, v5, vcc
	v_add_u32_e32 v5, 1, v3
	v_cmp_ge_u32_e32 vcc, v1, v2
	s_nop 1
	v_cndmask_b32_e32 v1, v3, v5, vcc
	v_mad_u64_u32 v[2:3], s[4:5], v2, v1, v[2:3]
	v_cmp_ne_u32_e32 vcc, v4, v2
	s_and_saveexec_b64 s[4:5], vcc
	s_xor_b64 s[4:5], exec, s[4:5]
	s_cbranch_execz .LBB0_194
	s_add_i32 s6, s24, 0x900
	s_lshl_b64 s[6:7], s[6:7], 2
	s_add_u32 s8, s36, 0x3400
	s_addc_u32 s9, s37, 0
	v_mad_u32_u24 v4, v1, v0, v0
	v_mov_b64_e32 v[2:3], s[8:9]
	flat_load_dword v0, v[2:3] sc1
	s_waitcnt vmcnt(0) lgkmcnt(0)
	v_cmp_lt_u32_e32 vcc, v0, v4
	s_and_saveexec_b64 s[6:7], vcc
	s_cbranch_execz .LBB0_193
	s_mov_b32 s25, 1
	s_mov_b64 s[10:11], 0
	s_branch .LBB0_185

.LBB0_189:
	s_andn2_b64 s[14:15], s[14:15], exec
	s_and_b64 s[20:21], s[20:21], exec
	s_or_b64 s[14:15], s[14:15], s[20:21]
	s_and_saveexec_b64 s[20:21], s[18:19]
	s_cbranch_execz .LBB0_184
	v_mov_b64_e32 v[2:3], s[8:9]
	flat_load_dword v0, v[2:3] sc1
	s_add_i32 s25, s25, 1
	s_or_b64 s[14:15], s[14:15], exec
	s_waitcnt vmcnt(0) lgkmcnt(0)
	v_cmp_ge_u32_e32 vcc, v0, v4
	s_orn2_b64 s[16:17], vcc, exec
	s_branch .LBB0_184

.LBB0_375:
	s_lshl_b32 s6, s6, 6
	s_add_i32 s82, s6, 0x500
	s_lshl_b64 s[8:9], s[82:83], 2
	s_add_u32 s8, s42, s8
	s_addc_u32 s9, s43, s9
	v_mov_b64_e32 v[4:5], s[8:9]
	flat_atomic_add v3, v[4:5], v228 sc0
	v_cvt_f32_u32_e32 v1, v2
	v_sub_u32_e32 v4, 0, v2
	v_rcp_iflag_f32_e32 v1, v1
	s_nop 0
	v_mul_f32_e32 v1, 0x4f7ffffe, v1
	v_cvt_u32_f32_e32 v1, v1
	v_mul_lo_u32 v4, v4, v1
	v_mul_hi_u32 v4, v1, v4
	v_add_u32_e32 v1, v1, v4
	s_waitcnt vmcnt(0) lgkmcnt(0)
	v_mul_hi_u32 v1, v3, v1
	v_mul_lo_u32 v4, v1, v2
	v_sub_u32_e32 v4, v3, v4
	v_cmp_ge_u32_e32 vcc, v4, v2
	v_add_u32_e32 v5, 1, v1
	s_nop 0
	v_cndmask_b32_e32 v1, v1, v5, vcc
	v_sub_u32_e32 v5, v4, v2
	v_cndmask_b32_e32 v4, v4, v5, vcc
	v_cmp_ge_u32_e32 vcc, v4, v2
	v_add_u32_e32 v4, 1, v1
	s_nop 0
	v_cndmask_b32_e32 v1, v1, v4, vcc
	v_add_u32_e32 v4, 1, v3
	v_mad_u64_u32 v[2:3], s[8:9], v2, v1, v[2:3]
	v_cmp_ne_u32_e32 vcc, v4, v2
	s_and_saveexec_b64 s[8:9], vcc
	s_xor_b64 s[8:9], exec, s[8:9]
	s_cbranch_execz .LBB0_388
	s_add_i32 s82, s6, 0x900
	s_lshl_b64 s[10:11], s[82:83], 2
	s_add_u32 s12, s42, 0x3400
	s_addc_u32 s13, s43, 0
	v_mad_u32_u24 v4, v1, v0, v0
	v_mov_b64_e32 v[2:3], s[12:13]
	flat_load_dword v0, v[2:3] sc1
	s_waitcnt vmcnt(0) lgkmcnt(0)
	v_cmp_lt_u32_e32 vcc, v0, v4
	s_and_saveexec_b64 s[10:11], vcc
	s_cbranch_execz .LBB0_387
	s_mov_b32 s7, 1
	s_mov_b64 s[14:15], 0
	s_branch .LBB0_379

.LBB0_383:
	s_andn2_b64 s[18:19], s[18:19], exec
	s_and_b64 s[24:25], s[24:25], exec
	s_or_b64 s[18:19], s[18:19], s[24:25]
	s_and_saveexec_b64 s[24:25], s[22:23]
	s_cbranch_execz .LBB0_378
	v_mov_b64_e32 v[2:3], s[12:13]
	flat_load_dword v0, v[2:3] sc1
	s_add_i32 s7, s7, 1
	s_or_b64 s[18:19], s[18:19], exec
	s_waitcnt vmcnt(0) lgkmcnt(0)
	v_cmp_ge_u32_e32 vcc, v0, v4
	s_orn2_b64 s[20:21], vcc, exec
	s_branch .LBB0_378

.LBB0_757:
	s_lshl_b32 s6, s6, 6
	s_add_i32 s82, s6, 0x500
	s_lshl_b64 s[8:9], s[82:83], 2
	s_add_u32 s8, s54, s8
	s_addc_u32 s9, s55, s9
	v_mov_b64_e32 v[4:5], s[8:9]
	flat_atomic_add v3, v[4:5], v228 sc0
	v_cvt_f32_u32_e32 v1, v2
	v_sub_u32_e32 v4, 0, v2
	v_rcp_iflag_f32_e32 v1, v1
	s_nop 0
	v_mul_f32_e32 v1, 0x4f7ffffe, v1
	v_cvt_u32_f32_e32 v1, v1
	v_mul_lo_u32 v4, v4, v1
	v_mul_hi_u32 v4, v1, v4
	v_add_u32_e32 v1, v1, v4
	s_waitcnt vmcnt(0) lgkmcnt(0)
	v_mul_hi_u32 v1, v3, v1
	v_mul_lo_u32 v4, v1, v2
	v_sub_u32_e32 v4, v3, v4
	v_cmp_ge_u32_e32 vcc, v4, v2
	v_add_u32_e32 v5, 1, v1
	s_nop 0
	v_cndmask_b32_e32 v1, v1, v5, vcc
	v_sub_u32_e32 v5, v4, v2
	v_cndmask_b32_e32 v4, v4, v5, vcc
	v_cmp_ge_u32_e32 vcc, v4, v2
	v_add_u32_e32 v4, 1, v1
	s_nop 0
	v_cndmask_b32_e32 v1, v1, v4, vcc
	v_add_u32_e32 v4, 1, v3
	v_mad_u64_u32 v[2:3], s[8:9], v2, v1, v[2:3]
	v_cmp_ne_u32_e32 vcc, v4, v2
	s_and_saveexec_b64 s[8:9], vcc
	s_xor_b64 s[12:13], exec, s[8:9]
	s_cbranch_execz .LBB0_770
	s_add_i32 s82, s6, 0x900
	s_lshl_b64 s[8:9], s[82:83], 2
	s_add_u32 s16, s54, 0x3400
	s_addc_u32 s17, s55, 0
	v_mad_u32_u24 v4, v1, v0, v0
	v_mov_b64_e32 v[2:3], s[16:17]
	flat_load_dword v0, v[2:3] sc1
	s_waitcnt vmcnt(0) lgkmcnt(0)
	v_cmp_lt_u32_e32 vcc, v0, v4
	s_and_saveexec_b64 s[14:15], vcc
	s_cbranch_execz .LBB0_769
	s_mov_b32 s7, 1
	s_mov_b64 s[18:19], 0
	s_branch .LBB0_761

.LBB0_765:
	s_andn2_b64 s[8:9], s[22:23], exec
	s_and_b64 s[10:11], s[28:29], exec
	s_or_b64 s[22:23], s[8:9], s[10:11]
	s_and_saveexec_b64 s[28:29], s[26:27]
	s_cbranch_execz .LBB0_760
	v_mov_b64_e32 v[2:3], s[16:17]
	flat_load_dword v0, v[2:3] sc1
	s_add_i32 s7, s7, 1
	s_or_b64 s[22:23], s[22:23], exec
	s_waitcnt vmcnt(0) lgkmcnt(0)
	v_cmp_ge_u32_e32 vcc, v0, v4
	s_orn2_b64 s[24:25], vcc, exec
	s_branch .LBB0_760

.LBB0_1123:
	s_lshl_b32 s6, s6, 6
	s_add_i32 s82, s6, 0x500
	s_lshl_b64 s[8:9], s[82:83], 2
	s_add_u32 s8, s50, s8
	s_addc_u32 s9, s51, s9
	v_mov_b64_e32 v[4:5], s[8:9]
	flat_atomic_add v3, v[4:5], v228 sc0
	v_cvt_f32_u32_e32 v1, v2
	v_sub_u32_e32 v4, 0, v2
	v_rcp_iflag_f32_e32 v1, v1
	s_nop 0
	v_mul_f32_e32 v1, 0x4f7ffffe, v1
	v_cvt_u32_f32_e32 v1, v1
	v_mul_lo_u32 v4, v4, v1
	v_mul_hi_u32 v4, v1, v4
	v_add_u32_e32 v1, v1, v4
	s_waitcnt vmcnt(0) lgkmcnt(0)
	v_mul_hi_u32 v1, v3, v1
	v_mul_lo_u32 v4, v1, v2
	v_sub_u32_e32 v4, v3, v4
	v_cmp_ge_u32_e32 vcc, v4, v2
	v_add_u32_e32 v5, 1, v1
	s_nop 0
	v_cndmask_b32_e32 v1, v1, v5, vcc
	v_sub_u32_e32 v5, v4, v2
	v_cndmask_b32_e32 v4, v4, v5, vcc
	v_cmp_ge_u32_e32 vcc, v4, v2
	v_add_u32_e32 v4, 1, v1
	s_nop 0
	v_cndmask_b32_e32 v1, v1, v4, vcc
	v_add_u32_e32 v4, 1, v3
	v_mad_u64_u32 v[2:3], s[8:9], v2, v1, v[2:3]
	v_cmp_ne_u32_e32 vcc, v4, v2
	s_and_saveexec_b64 s[8:9], vcc
	s_xor_b64 s[12:13], exec, s[8:9]
	s_cbranch_execz .LBB0_1136
	s_add_i32 s82, s6, 0x900
	s_lshl_b64 s[8:9], s[82:83], 2
	s_add_u32 s16, s50, 0x3400
	s_addc_u32 s17, s51, 0
	v_mad_u32_u24 v4, v1, v0, v0
	v_mov_b64_e32 v[2:3], s[16:17]
	flat_load_dword v0, v[2:3] sc1
	s_waitcnt vmcnt(0) lgkmcnt(0)
	v_cmp_lt_u32_e32 vcc, v0, v4
	s_and_saveexec_b64 s[14:15], vcc
	s_cbranch_execz .LBB0_1135
	s_mov_b32 s7, 1
	s_mov_b64 s[18:19], 0
	s_branch .LBB0_1127

.LBB0_1131:
	s_andn2_b64 s[8:9], s[22:23], exec
	s_and_b64 s[22:23], s[28:29], exec
	s_or_b64 s[22:23], s[8:9], s[22:23]
	s_and_saveexec_b64 s[28:29], s[26:27]
	s_cbranch_execz .LBB0_1126
	v_mov_b64_e32 v[2:3], s[16:17]
	flat_load_dword v0, v[2:3] sc1
	s_add_i32 s7, s7, 1
	s_or_b64 s[22:23], s[22:23], exec
	s_waitcnt vmcnt(0) lgkmcnt(0)
	v_cmp_ge_u32_e32 vcc, v0, v4
	s_orn2_b64 s[24:25], vcc, exec
	s_branch .LBB0_1126

.LBB0_1238:
	s_lshl_b32 s6, s6, 6
	s_add_i32 s82, s6, 0x500
	s_lshl_b64 s[8:9], s[82:83], 2
	s_add_u32 s8, s50, s8
	s_addc_u32 s9, s51, s9
	v_mov_b64_e32 v[4:5], s[8:9]
	flat_atomic_add v3, v[4:5], v228 sc0
	v_cvt_f32_u32_e32 v1, v2
	v_sub_u32_e32 v4, 0, v2
	v_rcp_iflag_f32_e32 v1, v1
	s_nop 0
	v_mul_f32_e32 v1, 0x4f7ffffe, v1
	v_cvt_u32_f32_e32 v1, v1
	v_mul_lo_u32 v4, v4, v1
	v_mul_hi_u32 v4, v1, v4
	v_add_u32_e32 v1, v1, v4
	s_waitcnt vmcnt(0) lgkmcnt(0)
	v_mul_hi_u32 v1, v3, v1
	v_mul_lo_u32 v4, v1, v2
	v_sub_u32_e32 v4, v3, v4
	v_cmp_ge_u32_e32 vcc, v4, v2
	v_add_u32_e32 v5, 1, v1
	s_nop 0
	v_cndmask_b32_e32 v1, v1, v5, vcc
	v_sub_u32_e32 v5, v4, v2
	v_cndmask_b32_e32 v4, v4, v5, vcc
	v_cmp_ge_u32_e32 vcc, v4, v2
	v_add_u32_e32 v4, 1, v1
	s_nop 0
	v_cndmask_b32_e32 v1, v1, v4, vcc
	v_add_u32_e32 v4, 1, v3
	v_mad_u64_u32 v[2:3], s[8:9], v2, v1, v[2:3]
	v_cmp_ne_u32_e32 vcc, v4, v2
	s_and_saveexec_b64 s[8:9], vcc
	s_xor_b64 s[10:11], exec, s[8:9]
	s_cbranch_execz .LBB0_1251
	s_add_i32 s82, s6, 0x900
	s_lshl_b64 s[8:9], s[82:83], 2
	s_add_u32 s14, s50, 0x3400
	s_addc_u32 s15, s51, 0
	v_mad_u32_u24 v4, v1, v0, v0
	v_mov_b64_e32 v[2:3], s[14:15]
	flat_load_dword v0, v[2:3] sc1
	s_waitcnt vmcnt(0) lgkmcnt(0)
	v_cmp_lt_u32_e32 vcc, v0, v4
	s_and_saveexec_b64 s[12:13], vcc
	s_cbranch_execz .LBB0_1250
	s_mov_b32 s7, 1
	s_mov_b64 s[16:17], 0
	s_branch .LBB0_1242

.LBB0_1246:
	s_andn2_b64 s[8:9], s[20:21], exec
	s_and_b64 s[20:21], s[26:27], exec
	s_or_b64 s[20:21], s[8:9], s[20:21]
	s_and_saveexec_b64 s[26:27], s[24:25]
	s_cbranch_execz .LBB0_1241
	v_mov_b64_e32 v[2:3], s[14:15]
	flat_load_dword v0, v[2:3] sc1
	s_add_i32 s7, s7, 1
	s_or_b64 s[20:21], s[20:21], exec
	s_waitcnt vmcnt(0) lgkmcnt(0)
	v_cmp_ge_u32_e32 vcc, v0, v4
	s_orn2_b64 s[22:23], vcc, exec
	s_branch .LBB0_1241
